# up-GEMM phases: intra-XCD start stagger (4 groups of 8 CUs per XCD, 2us steps) to split each L2's epilogue store burst, on top of v21
# speedup vs baseline: 1.0069x; 1.0027x over previous
; #define TIDX opaque_tid()
; #define STAGE_A(P, h, kt) { const bf16_t* g_ = gA0 + (size_t)(h) * 2 * a64 + (kt) * 64; glds16(g_, (char*)(P) + tid * 16); glds16(g_ + a64, (char*)(P) + tid * 16 + 8192); }
; #define STAGE_B(P, h, kt) { const bf16_t* g_ = gB0 + (size_t)(h) * 2 * b64 + (kt) * 64; glds16(g_, (char*)(P) + tid * 16); glds16(g_ + b64, (char*)(P) + tid * 16 + 8192); }
; template <bool ISSUE_ONLY, bool PRE_ISSUED>
; __device__ __forceinline__ void gemm_core(f32x4 (&acc)[2][2][4][2], const bf16_t* __restrict__ A, int lda, const bf16_t* __restrict__ Bt, int ldb, int K, char* ldsc) {
;   bf16_t* shm = (bf16_t*)ldsc;
;   const int tid = TIDX, wid = tid >> 6, lane = tid & 63, wr = wid >> 2, wc = wid & 3, fr = lane & 15, fq = lane >> 4;
;   int sr0, sc0;
;   g8_stage_rc(tid * 16, sr0, sc0);
;   const bf16_t* gA0 = A + (size_t)sr0 * lda + sc0;
;   const bf16_t* gB0 = Bt + (size_t)sr0 * ldb + sc0;
;   const size_t a64 = (size_t)64 * lda, b64 = (size_t)64 * ldb;
;   const int lane_off = (fr * 64 + fq * 16) ^ ((((fr * 64 + fq * 16) >> 9) & 1) << 5);
;   const char* ldA = ldsc + wr * 8192 + lane_off;
;   const char* ldB = ldsc + 65536 + wc * 4096 + lane_off;
;     ...
;   bf16x8 At[4][2], B0[2][2], B1[2][2];
;   const int nt = K >> 6;
;   if (!PRE_ISSUED) {
;     STAGE_B(SB(0, 0), 0, 0); STAGE_A(SA(0, 0), 0, 0);
;     STAGE_B(SB(0, 1), 1, 0); STAGE_A(SA(0, 1), 1, 0);
;   }
; template <class Epi> __device__ __forceinline__ void gemm_phase(const bf16_t* A, int lda, const bf16_t* Bt, int ldb, int K, int TN, char* lds, Epi&& epi) {
;   TileIt it; it.init(TN);
;   bool have = it.next();
;   f32x4 acc[2][2][4][2];
;   if (have) gemm_core<true, false>(acc, A + (size_t)it.tm * 256 * lda, lda, Bt + (size_t)it.tn * 256 * ldb, ldb, K, lds);
.LBB0_643:
	s_andn2_b64 vcc, exec, s[30:31]
	s_cbranch_vccnz .LBB0_660
	s_bfe_u32 s16, s2, 0x20003
	s_cmp_eq_u32 s16, 0
	s_cbranch_scc1 .Lmy_stag_done
.Lmy_stag_loop:
	s_sleep 72
	s_sub_u32 s16, s16, 1
	s_cmp_lg_u32 s16, 0
	s_cbranch_scc1 .Lmy_stag_loop
.Lmy_stag_done:
	v_readlane_b32 s16, v255, 3
	s_cmp_eq_u32 s16, 8
	s_cselect_b64 s[16:17], -1, 0
	s_waitcnt vmcnt(0)
	v_cndmask_b32_e64 v0, 0, 1, s[16:17]
	v_readlane_b32 s16, v254, 63
	v_readlane_b32 s17, v255, 0
	s_and_b64 s[16:17], s[16:17], exec
	v_readfirstlane_b32 s17, v0
	v_mov_b32 v0, v179
	s_cselect_b32 s16, 2, 0
	v_ashrrev_i32_e32 v1, 31, v0
	v_lshrrev_b32_e32 v1, 26, v1
	v_lshlrev_b32_e32 v6, 4, v0
	v_add_u32_e32 v1, v0, v1
	v_bfe_i32 v0, v0, 27, 1
	v_lshrrev_b32_e32 v0, 22, v0
	v_add_u32_e32 v0, v6, v0
	s_or_b32 s16, s17, s16
	v_and_b32_e32 v0, 0xfffffc00, v0
	s_mul_i32 s16, s16, 0xb00000
	v_sub_u32_e32 v0, v6, v0
	s_add_u32 s63, s10, s16
	v_lshrrev_b32_e32 v2, 4, v0
	s_addc_u32 s64, s11, 0
	s_lshl_b32 s16, s34, 4
	s_and_b32 s1, s1, 15
	v_bitop3_b32 v2, v2, v0, 32 bitop3:0x6c
	v_ashrrev_i32_e32 v0, 31, v0
	s_or_b32 s34, s16, s1
	v_ashrrev_i32_e32 v1, 6, v1
	v_lshrrev_b32_e32 v0, 26, v0
	s_ashr_i32 s35, s34, 31
	v_lshlrev_b32_e32 v3, 3, v1
	v_add_u32_e32 v0, v2, v0
	s_lshl_b64 s[16:17], s[34:35], 19
	v_readlane_b32 s30, v252, 34
	v_and_b32_e32 v3, -16, v3
	v_ashrrev_i32_e32 v4, 6, v0
	v_readlane_b32 s31, v252, 35
	s_add_u32 s16, s30, s16
	v_add_u32_e32 v0, v4, v3
	v_mul_i32_i24_e32 v3, 64, v4
	s_addc_u32 s17, s31, s17
	s_ashr_i32 s1, s0, 31
	v_lshlrev_b32_e32 v1, 5, v1
	v_sub_u32_e32 v2, v2, v3
	s_lshl_b64 s[30:31], s[0:1], 19
	v_and_b32_e32 v1, 32, v1
	v_ashrrev_i16_sdwa v2, v217, sext(v2) dst_sel:DWORD dst_unused:UNUSED_PAD src0_sel:DWORD src1_sel:BYTE_0
	s_add_u32 s30, s63, s30
	v_add_u32_sdwa v2, v1, sext(v2) dst_sel:DWORD dst_unused:UNUSED_PAD src0_sel:DWORD src1_sel:WORD_0
	v_ashrrev_i32_e32 v1, 31, v0
	s_addc_u32 s31, s64, s31
	v_lshlrev_b64 v[0:1], 11, v[0:1]
	v_ashrrev_i32_e32 v3, 31, v2
	v_lshl_add_u64 v[4:5], s[16:17], 0, v[0:1]
	v_lshlrev_b64 v[2:3], 1, v[2:3]
	v_lshl_add_u64 v[0:1], s[30:31], 0, v[0:1]
	v_lshl_add_u64 v[4:5], v[4:5], 0, v[2:3]
	v_lshl_add_u64 v[0:1], v[0:1], 0, v[2:3]
	v_add_u32_e32 v2, 0x10000, v6
	v_add_u32_e32 v7, 0x12000, v6
	v_readfirstlane_b32 s1, v2
	s_mov_b32 m0, s1
	s_mov_b64 s[16:17], 0x20000
	v_readfirstlane_b32 s1, v7
	global_load_lds_dwordx4 v[0:1], off
	v_lshl_add_u64 v[2:3], v[0:1], 0, s[16:17]
	s_mov_b32 m0, s1
	v_readfirstlane_b32 s1, v6
	v_add_u32_e32 v7, 0x2000, v6
	global_load_lds_dwordx4 v[2:3], off
	s_mov_b32 m0, s1
	v_readfirstlane_b32 s1, v7
	v_add_u32_e32 v7, 0x14000, v6
	global_load_lds_dwordx4 v[4:5], off
	v_lshl_add_u64 v[2:3], v[4:5], 0, s[16:17]
	s_mov_b32 m0, s1
	s_mov_b64 s[16:17], 0x40000
	v_readfirstlane_b32 s1, v7
	global_load_lds_dwordx4 v[2:3], off
	v_lshl_add_u64 v[2:3], v[0:1], 0, s[16:17]
	s_mov_b32 m0, s1
	s_mov_b64 s[30:31], 0x60000
	global_load_lds_dwordx4 v[2:3], off
	v_add_u32_e32 v2, 0x16000, v6
	v_lshl_add_u64 v[0:1], v[0:1], 0, s[30:31]
	v_readfirstlane_b32 s1, v2
	v_add_u32_e32 v2, 0x4000, v6
	s_mov_b32 m0, s1
	v_readfirstlane_b32 s1, v2
	v_add_u32_e32 v2, 0x6000, v6
	global_load_lds_dwordx4 v[0:1], off
	v_lshl_add_u64 v[0:1], v[4:5], 0, s[16:17]
	s_mov_b32 m0, s1
	v_readfirstlane_b32 s1, v2
	global_load_lds_dwordx4 v[0:1], off
	v_lshl_add_u64 v[0:1], v[4:5], 0, s[30:31]
	s_mov_b32 m0, s1
	s_nop 0
	global_load_lds_dwordx4 v[0:1], off
	s_branch .LBB0_646
